# v63 + attention M segment: K-fragment reads two ahead, early V fragment reads, counted lgkmcnt waits in P.V
# baseline (speedup 1.0000x reference)
; template <int D0> __device__ __forceinline__ void pv_one(f32x16& od, int vb, bf16x8 pa0, bf16x8 pa1, bf16x8 pa2, bf16x8 pa3) {
;   const s16x4 l0 = tr_read<v_rd_off(D0, 0, 0)>(vb), h0 = tr_read<v_rd_off(D0, 0, 1)>(vb), l1 = tr_read<v_rd_off(D0, 1, 0)>(vb), h1 = tr_read<v_rd_off(D0, 1, 1)>(vb);
;   const s16x4 l2 = tr_read<v_rd_off(D0, 2, 0)>(vb), h2 = tr_read<v_rd_off(D0, 2, 1)>(vb), l3 = tr_read<v_rd_off(D0, 3, 0)>(vb), h3 = tr_read<v_rd_off(D0, 3, 1)>(vb);
;   asm volatile("s_waitcnt lgkmcnt(0)" ::: "memory"); SBAR();
;     ...
;   od = __builtin_amdgcn_mfma_f32_32x32x16_bf16(pa0, PK(l0, h0), od, 0, 0, 0);
;   od = __builtin_amdgcn_mfma_f32_32x32x16_bf16(pa1, PK(l1, h1), od, 0, 0, 0);
;   od = __builtin_amdgcn_mfma_f32_32x32x16_bf16(pa2, PK(l2, h2), od, 0, 0, 0);
;   od = __builtin_amdgcn_mfma_f32_32x32x16_bf16(pa3, PK(l3, h3), od, 0, 0, 0);
;     ...
; }
; __device__ __forceinline__ void pv_d0(f32x16* o, int vb, bf16x8 pa0, bf16x8 pa1, bf16x8 pa2, bf16x8 pa3) {
;   pv_one<0>(o[0], vb, pa0, pa1, pa2, pa3); pv_one<1>(o[1], vb, pa0, pa1, pa2, pa3); pv_one<2>(o[2], vb, pa0, pa1, pa2, pa3); pv_one<3>(o[3], vb, pa0, pa1, pa2, pa3);
; }
; __device__ __forceinline__ void qkt_c(f32x16& p0, f32x16& p1, const char* Ks, const bf16x8* qr, const f32x16& negm, int r32, int hi) {
; #pragma unroll
;   for (int d0 = 0; d0 < 4; ++d0) { const int cb = (d0 * 16 + hi * 8) * 2;
;     bf16x8 b0 = *reinterpret_cast<const bf16x8*>(Ks + KSWZ(r32, cb));
;     bf16x8 b1 = *reinterpret_cast<const bf16x8*>(Ks + KSWZ(32 + r32, cb));
;     if (d0 == 0) { p0 = __builtin_amdgcn_mfma_f32_32x32x16_bf16(b0, qr[0], negm, 0, 0, 0); p1 = __builtin_amdgcn_mfma_f32_32x32x16_bf16(b1, qr[0], negm, 0, 0, 0); }
;     else { p0 = __builtin_amdgcn_mfma_f32_32x32x16_bf16(b0, qr[d0], p0, 0, 0, 0); p1 = __builtin_amdgcn_mfma_f32_32x32x16_bf16(b1, qr[d0], p1, 0, 0, 0); } }
; }
; template <int R> __device__ __forceinline__ void bias_r(f32x16& p0, f32x16& p1, float dq, float nslope) {
;   constexpr int C0 = (R & 3) + 8 * (R >> 2);
;   float x0, x1, a0 = p0[R], a1 = p1[R];
;   asm("v_sub_f32_e32 %0, %1, %2" : "=v"(x0) : "n"(__builtin_bit_cast(int, (float)C0)), "v"(dq));
;   asm("v_sub_f32_e32 %0, %1, %2" : "=v"(x1) : "n"(__builtin_bit_cast(int, (float)(C0 + 32))), "v"(dq));
;   asm("v_fma_f32 %0, %1, |%2|, %0" : "+v"(a0) : "v"(nslope), "v"(x0));
;   asm("v_fma_f32 %0, %1, |%2|, %0" : "+v"(a1) : "v"(nslope), "v"(x1));
.LBB0_364:
	ds_read_b128 v[114:117], v195 offset:32768
	ds_read_b128 v[212:215], v195 offset:40960
	ds_read_b128 v[216:219], v196 offset:32768
	s_and_b64 vcc, exec, s[14:15]
	s_waitcnt lgkmcnt(2)
	v_mfma_f32_32x32x16_bf16 v[98:113], v[114:117], v[130:133], v[82:97]
	ds_read_b128 v[220:223], v196 offset:40960
	s_waitcnt lgkmcnt(2)
	v_mfma_f32_32x32x16_bf16 v[114:129], v[212:215], v[130:133], v[82:97]
	ds_read_b128 v[212:215], v197 offset:32768
	s_waitcnt lgkmcnt(2)
	v_mfma_f32_32x32x16_bf16 v[98:113], v[216:219], v[134:137], v[98:113]
	ds_read_b128 v[216:219], v197 offset:40960
	s_waitcnt lgkmcnt(2)
	v_mfma_f32_32x32x16_bf16 v[114:129], v[220:223], v[134:137], v[114:129]
	ds_read_b128 v[220:223], v198 offset:32768
	s_waitcnt lgkmcnt(2)
	v_mfma_f32_32x32x16_bf16 v[98:113], v[212:215], v[138:141], v[98:113]
	ds_read_b128 v[212:215], v198 offset:40960
	s_waitcnt lgkmcnt(2)
	v_mfma_f32_32x32x16_bf16 v[114:129], v[216:219], v[138:141], v[114:129]
	s_cbranch_vccnz .Lqk_tail_0
	ds_read_b64_tr_b16 v[204:205], v194 offset:0
	ds_read_b64_tr_b16 v[206:207], v194 offset:0x800
	ds_read_b64_tr_b16 v[208:209], v194 offset:0x1000
	ds_read_b64_tr_b16 v[210:211], v194 offset:0x1800
	s_waitcnt lgkmcnt(5)
	v_mfma_f32_32x32x16_bf16 v[98:113], v[220:223], v[142:145], v[98:113]
	s_waitcnt lgkmcnt(4)
	v_mfma_f32_32x32x16_bf16 v[114:129], v[212:215], v[142:145], v[114:129]
	s_add_i32 s72, s22, s46
	s_cmp_lt_i32 s46, s23
	s_cselect_b32 s14, s72, s39
	s_lshl_b32 s14, s14, 6
	v_cvt_f32_i32_e32 v0, s14
	v_sub_f32_e32 v0, v192, v0
	ds_read_b64_tr_b16 v[212:213], v194 offset:0x2000
	ds_read_b64_tr_b16 v[214:215], v194 offset:0x2800
	ds_read_b64_tr_b16 v[216:217], v194 offset:0x3000
	ds_read_b64_tr_b16 v[218:219], v194 offset:0x3800
	s_waitcnt lgkmcnt(6)
	v_mfma_f32_32x32x16_bf16 v[64:79], v[2:5], v[204:207], v[64:79]
	v_sub_f32_e32 v14, 0, v0
	v_sub_f32_e32 v15, 0x42000000, v0
	v_fma_f32 v98, v81, |v14|, v98
	v_sub_f32_e32 v14, 0x3f800000, v0
	ds_read_b64_tr_b16 v[204:205], v194 offset:0x200
	ds_read_b64_tr_b16 v[206:207], v194 offset:0xa00
	s_waitcnt lgkmcnt(6)
	v_mfma_f32_32x32x16_bf16 v[64:79], v[6:9], v[208:211], v[64:79]
	v_fma_f32 v114, v81, |v15|, v114
	v_sub_f32_e32 v15, 0x42040000, v0
	v_fma_f32 v99, v81, |v14|, v99
	v_sub_f32_e32 v14, 0x40000000, v0
	ds_read_b64_tr_b16 v[208:209], v194 offset:0x1200
	ds_read_b64_tr_b16 v[210:211], v194 offset:0x1a00
	s_waitcnt lgkmcnt(6)
	v_mfma_f32_32x32x16_bf16 v[64:79], v[10:13], v[212:215], v[64:79]
	v_fma_f32 v115, v81, |v15|, v115
	v_sub_f32_e32 v15, 0x42080000, v0
	v_fma_f32 v100, v81, |v14|, v100
	v_sub_f32_e32 v14, 0x40400000, v0
	ds_read_b64_tr_b16 v[212:213], v194 offset:0x2200
	ds_read_b64_tr_b16 v[214:215], v194 offset:0x2a00
	ds_read_b64_tr_b16 v[220:221], v194 offset:0x3200
	ds_read_b64_tr_b16 v[222:223], v194 offset:0x3a00
	s_waitcnt lgkmcnt(8)
	v_mfma_f32_32x32x16_bf16 v[64:79], v[162:165], v[216:219], v[64:79]
	v_fma_f32 v116, v81, |v15|, v116
	v_sub_f32_e32 v15, 0x420c0000, v0
	v_fma_f32 v101, v81, |v14|, v101
	v_sub_f32_e32 v14, 0x41000000, v0
	s_waitcnt lgkmcnt(6)
	v_mfma_f32_32x32x16_bf16 v[48:63], v[2:5], v[204:207], v[48:63]
	v_fma_f32 v117, v81, |v15|, v117
	v_sub_f32_e32 v15, 0x42200000, v0
	v_fma_f32 v102, v81, |v14|, v102
	v_sub_f32_e32 v14, 0x41100000, v0
	ds_read_b64_tr_b16 v[204:205], v194 offset:0x400
	ds_read_b64_tr_b16 v[206:207], v194 offset:0xc00
	s_waitcnt lgkmcnt(6)
	v_mfma_f32_32x32x16_bf16 v[48:63], v[6:9], v[208:211], v[48:63]
	v_fma_f32 v118, v81, |v15|, v118
	v_sub_f32_e32 v15, 0x42240000, v0
	v_fma_f32 v103, v81, |v14|, v103
	v_sub_f32_e32 v14, 0x41200000, v0
	ds_read_b64_tr_b16 v[208:209], v194 offset:0x1400
	ds_read_b64_tr_b16 v[210:211], v194 offset:0x1c00
	s_waitcnt lgkmcnt(6)
	v_mfma_f32_32x32x16_bf16 v[48:63], v[10:13], v[212:215], v[48:63]
	v_fma_f32 v119, v81, |v15|, v119
	v_sub_f32_e32 v15, 0x42280000, v0
	v_fma_f32 v104, v81, |v14|, v104
	v_sub_f32_e32 v14, 0x41300000, v0
	ds_read_b64_tr_b16 v[212:213], v194 offset:0x2400
	ds_read_b64_tr_b16 v[214:215], v194 offset:0x2c00
	ds_read_b64_tr_b16 v[216:217], v194 offset:0x3400
	ds_read_b64_tr_b16 v[218:219], v194 offset:0x3c00
	s_waitcnt lgkmcnt(8)
	v_mfma_f32_32x32x16_bf16 v[48:63], v[162:165], v[220:223], v[48:63]
	v_fma_f32 v120, v81, |v15|, v120
	v_sub_f32_e32 v15, 0x422c0000, v0
	v_fma_f32 v105, v81, |v14|, v105
	v_sub_f32_e32 v14, 0x41800000, v0
	s_waitcnt lgkmcnt(6)
	v_mfma_f32_32x32x16_bf16 v[32:47], v[2:5], v[204:207], v[32:47]
	v_fma_f32 v121, v81, |v15|, v121
	v_sub_f32_e32 v15, 0x42400000, v0
	v_fma_f32 v106, v81, |v14|, v106
	v_sub_f32_e32 v14, 0x41880000, v0
	ds_read_b64_tr_b16 v[204:205], v194 offset:0x600
	ds_read_b64_tr_b16 v[206:207], v194 offset:0xe00
	s_waitcnt lgkmcnt(6)
	v_mfma_f32_32x32x16_bf16 v[32:47], v[6:9], v[208:211], v[32:47]
	v_fma_f32 v122, v81, |v15|, v122
	v_sub_f32_e32 v15, 0x42440000, v0
	v_fma_f32 v107, v81, |v14|, v107
	v_sub_f32_e32 v14, 0x41900000, v0
	ds_read_b64_tr_b16 v[208:209], v194 offset:0x1600
	ds_read_b64_tr_b16 v[210:211], v194 offset:0x1e00
	s_waitcnt lgkmcnt(6)
	v_mfma_f32_32x32x16_bf16 v[32:47], v[10:13], v[212:215], v[32:47]
	v_fma_f32 v123, v81, |v15|, v123
	v_sub_f32_e32 v15, 0x42480000, v0
	v_fma_f32 v108, v81, |v14|, v108
	v_sub_f32_e32 v14, 0x41980000, v0
	ds_read_b64_tr_b16 v[212:213], v194 offset:0x2600
	ds_read_b64_tr_b16 v[214:215], v194 offset:0x2e00
	ds_read_b64_tr_b16 v[220:221], v194 offset:0x3600
	ds_read_b64_tr_b16 v[222:223], v194 offset:0x3e00
	s_waitcnt lgkmcnt(8)
	v_mfma_f32_32x32x16_bf16 v[32:47], v[162:165], v[216:219], v[32:47]
	v_fma_f32 v124, v81, |v15|, v124
	v_sub_f32_e32 v15, 0x424c0000, v0
	v_fma_f32 v109, v81, |v14|, v109
	v_sub_f32_e32 v14, 0x41c00000, v0
	s_waitcnt lgkmcnt(6)
	v_mfma_f32_32x32x16_bf16 v[16:31], v[2:5], v[204:207], v[16:31]
	v_fma_f32 v125, v81, |v15|, v125
	v_sub_f32_e32 v15, 0x42600000, v0
	v_fma_f32 v110, v81, |v14|, v110
	v_sub_f32_e32 v14, 0x41c80000, v0
	s_waitcnt lgkmcnt(4)
	v_mfma_f32_32x32x16_bf16 v[16:31], v[6:9], v[208:211], v[16:31]
	v_fma_f32 v126, v81, |v15|, v126
	v_sub_f32_e32 v15, 0x42640000, v0
	v_fma_f32 v111, v81, |v14|, v111
	v_sub_f32_e32 v14, 0x41d00000, v0
	s_waitcnt lgkmcnt(2)
	v_mfma_f32_32x32x16_bf16 v[16:31], v[10:13], v[212:215], v[16:31]
	v_fma_f32 v127, v81, |v15|, v127
	v_sub_f32_e32 v15, 0x42680000, v0
	v_fma_f32 v112, v81, |v14|, v112
	v_sub_f32_e32 v14, 0x41d80000, v0
	s_waitcnt lgkmcnt(0)
	v_mfma_f32_32x32x16_bf16 v[16:31], v[162:165], v[220:223], v[16:31]
	v_sub_f32_e32 v0, 0x426c0000, v0
	v_fma_f32 v128, v81, |v15|, v128
	v_fma_f32 v113, v81, |v14|, v113
	v_fma_f32 v129, v81, |v0|, v129
	s_barrier
	s_branch .Lafter_bias_0
.Lqk_tail_0:
	s_waitcnt lgkmcnt(1)
	v_mfma_f32_32x32x16_bf16 v[98:113], v[220:223], v[142:145], v[98:113]
	s_waitcnt lgkmcnt(0)
	v_mfma_f32_32x32x16_bf16 v[114:129], v[212:215], v[142:145], v[114:129]
	s_nop 0

; template <int D0> __device__ __forceinline__ void pv_one(f32x16& od, int vb, bf16x8 pa0, bf16x8 pa1, bf16x8 pa2, bf16x8 pa3) {
;   const s16x4 l0 = tr_read<v_rd_off(D0, 0, 0)>(vb), h0 = tr_read<v_rd_off(D0, 0, 1)>(vb), l1 = tr_read<v_rd_off(D0, 1, 0)>(vb), h1 = tr_read<v_rd_off(D0, 1, 1)>(vb);
;   const s16x4 l2 = tr_read<v_rd_off(D0, 2, 0)>(vb), h2 = tr_read<v_rd_off(D0, 2, 1)>(vb), l3 = tr_read<v_rd_off(D0, 3, 0)>(vb), h3 = tr_read<v_rd_off(D0, 3, 1)>(vb);
;   asm volatile("s_waitcnt lgkmcnt(0)" ::: "memory"); SBAR();
;     ...
;   od = __builtin_amdgcn_mfma_f32_32x32x16_bf16(pa0, PK(l0, h0), od, 0, 0, 0);
;   od = __builtin_amdgcn_mfma_f32_32x32x16_bf16(pa1, PK(l1, h1), od, 0, 0, 0);
;   od = __builtin_amdgcn_mfma_f32_32x32x16_bf16(pa2, PK(l2, h2), od, 0, 0, 0);
;   od = __builtin_amdgcn_mfma_f32_32x32x16_bf16(pa3, PK(l3, h3), od, 0, 0, 0);
;     ...
; }
; __device__ __forceinline__ void pv_d0(f32x16* o, int vb, bf16x8 pa0, bf16x8 pa1, bf16x8 pa2, bf16x8 pa3) {
;   pv_one<0>(o[0], vb, pa0, pa1, pa2, pa3); pv_one<1>(o[1], vb, pa0, pa1, pa2, pa3); pv_one<2>(o[2], vb, pa0, pa1, pa2, pa3); pv_one<3>(o[3], vb, pa0, pa1, pa2, pa3);
; }
; __device__ __forceinline__ void qkt_c(f32x16& p0, f32x16& p1, const char* Ks, const bf16x8* qr, const f32x16& negm, int r32, int hi) {
; #pragma unroll
;   for (int d0 = 0; d0 < 4; ++d0) { const int cb = (d0 * 16 + hi * 8) * 2;
;     bf16x8 b0 = *reinterpret_cast<const bf16x8*>(Ks + KSWZ(r32, cb));
;     bf16x8 b1 = *reinterpret_cast<const bf16x8*>(Ks + KSWZ(32 + r32, cb));
;     if (d0 == 0) { p0 = __builtin_amdgcn_mfma_f32_32x32x16_bf16(b0, qr[0], negm, 0, 0, 0); p1 = __builtin_amdgcn_mfma_f32_32x32x16_bf16(b1, qr[0], negm, 0, 0, 0); }
;     else { p0 = __builtin_amdgcn_mfma_f32_32x32x16_bf16(b0, qr[d0], p0, 0, 0, 0); p1 = __builtin_amdgcn_mfma_f32_32x32x16_bf16(b1, qr[d0], p1, 0, 0, 0); } }
; }
; template <int R> __device__ __forceinline__ void bias_r(f32x16& p0, f32x16& p1, float dq, float nslope) {
;   constexpr int C0 = (R & 3) + 8 * (R >> 2);
;   float x0, x1, a0 = p0[R], a1 = p1[R];
;   asm("v_sub_f32_e32 %0, %1, %2" : "=v"(x0) : "n"(__builtin_bit_cast(int, (float)C0)), "v"(dq));
;   asm("v_sub_f32_e32 %0, %1, %2" : "=v"(x1) : "n"(__builtin_bit_cast(int, (float)(C0 + 32))), "v"(dq));
;   asm("v_fma_f32 %0, %1, |%2|, %0" : "+v"(a0) : "v"(nslope), "v"(x0));
;   asm("v_fma_f32 %0, %1, |%2|, %0" : "+v"(a1) : "v"(nslope), "v"(x1));
.LBB0_379:
	s_waitcnt lgkmcnt(0)
	s_barrier
	ds_read_b128 v[114:117], v195 offset:49152
	ds_read_b128 v[212:215], v195 offset:57344
	ds_read_b128 v[216:219], v196 offset:49152
	s_andn2_b64 vcc, exec, s[14:15]
	s_waitcnt lgkmcnt(2)
	v_mfma_f32_32x32x16_bf16 v[98:113], v[114:117], v[130:133], v[82:97]
	ds_read_b128 v[220:223], v196 offset:57344
	s_waitcnt lgkmcnt(2)
	v_mfma_f32_32x32x16_bf16 v[114:129], v[212:215], v[130:133], v[82:97]
	ds_read_b128 v[212:215], v197 offset:49152
	s_waitcnt lgkmcnt(2)
	v_mfma_f32_32x32x16_bf16 v[98:113], v[216:219], v[134:137], v[98:113]
	ds_read_b128 v[216:219], v197 offset:57344
	s_waitcnt lgkmcnt(2)
	v_mfma_f32_32x32x16_bf16 v[114:129], v[220:223], v[134:137], v[114:129]
	ds_read_b128 v[220:223], v198 offset:49152
	s_waitcnt lgkmcnt(2)
	v_mfma_f32_32x32x16_bf16 v[98:113], v[212:215], v[138:141], v[98:113]
	ds_read_b128 v[212:215], v198 offset:57344
	s_waitcnt lgkmcnt(2)
	v_mfma_f32_32x32x16_bf16 v[114:129], v[216:219], v[138:141], v[114:129]
	s_cbranch_vccnz .Lqk_tail_1
	ds_read_b64_tr_b16 v[204:205], v193 offset:0
	ds_read_b64_tr_b16 v[206:207], v193 offset:0x800
	ds_read_b64_tr_b16 v[208:209], v193 offset:0x1000
	ds_read_b64_tr_b16 v[210:211], v193 offset:0x1800
	s_waitcnt lgkmcnt(5)
	v_mfma_f32_32x32x16_bf16 v[98:113], v[220:223], v[142:145], v[98:113]
	s_waitcnt lgkmcnt(4)
	v_mfma_f32_32x32x16_bf16 v[114:129], v[212:215], v[142:145], v[114:129]
	s_add_i32 s46, s47, -1
	s_add_i32 s72, s72, 1
	s_add_i32 s14, s39, -1
	s_cmp_lt_i32 s46, s23
	s_cselect_b32 s14, s72, s14
	s_lshl_b32 s14, s14, 6
	v_cvt_f32_i32_e32 v0, s14
	v_sub_f32_e32 v0, v192, v0
	ds_read_b64_tr_b16 v[212:213], v193 offset:0x2000
	ds_read_b64_tr_b16 v[214:215], v193 offset:0x2800
	ds_read_b64_tr_b16 v[216:217], v193 offset:0x3000
	ds_read_b64_tr_b16 v[218:219], v193 offset:0x3800
	s_waitcnt lgkmcnt(6)
	v_mfma_f32_32x32x16_bf16 v[64:79], v[2:5], v[204:207], v[64:79]
	v_sub_f32_e32 v14, 0, v0
	v_sub_f32_e32 v15, 0x42000000, v0
	v_fma_f32 v98, v81, |v14|, v98
	v_sub_f32_e32 v14, 0x3f800000, v0
	ds_read_b64_tr_b16 v[204:205], v193 offset:0x200
	ds_read_b64_tr_b16 v[206:207], v193 offset:0xa00
	s_waitcnt lgkmcnt(6)
	v_mfma_f32_32x32x16_bf16 v[64:79], v[6:9], v[208:211], v[64:79]
	v_fma_f32 v114, v81, |v15|, v114
	v_sub_f32_e32 v15, 0x42040000, v0
	v_fma_f32 v99, v81, |v14|, v99
	v_sub_f32_e32 v14, 0x40000000, v0
	ds_read_b64_tr_b16 v[208:209], v193 offset:0x1200
	ds_read_b64_tr_b16 v[210:211], v193 offset:0x1a00
	s_waitcnt lgkmcnt(6)
	v_mfma_f32_32x32x16_bf16 v[64:79], v[10:13], v[212:215], v[64:79]
	v_fma_f32 v115, v81, |v15|, v115
	v_sub_f32_e32 v15, 0x42080000, v0
	v_fma_f32 v100, v81, |v14|, v100
	v_sub_f32_e32 v14, 0x40400000, v0
	ds_read_b64_tr_b16 v[212:213], v193 offset:0x2200
	ds_read_b64_tr_b16 v[214:215], v193 offset:0x2a00
	ds_read_b64_tr_b16 v[220:221], v193 offset:0x3200
	ds_read_b64_tr_b16 v[222:223], v193 offset:0x3a00
	s_waitcnt lgkmcnt(8)
	v_mfma_f32_32x32x16_bf16 v[64:79], v[162:165], v[216:219], v[64:79]
	v_fma_f32 v116, v81, |v15|, v116
	v_sub_f32_e32 v15, 0x420c0000, v0
	v_fma_f32 v101, v81, |v14|, v101
	v_sub_f32_e32 v14, 0x41000000, v0
	s_waitcnt lgkmcnt(6)
	v_mfma_f32_32x32x16_bf16 v[48:63], v[2:5], v[204:207], v[48:63]
	v_fma_f32 v117, v81, |v15|, v117
	v_sub_f32_e32 v15, 0x42200000, v0
	v_fma_f32 v102, v81, |v14|, v102
	v_sub_f32_e32 v14, 0x41100000, v0
	ds_read_b64_tr_b16 v[204:205], v193 offset:0x400
	ds_read_b64_tr_b16 v[206:207], v193 offset:0xc00
	s_waitcnt lgkmcnt(6)
	v_mfma_f32_32x32x16_bf16 v[48:63], v[6:9], v[208:211], v[48:63]
	v_fma_f32 v118, v81, |v15|, v118
	v_sub_f32_e32 v15, 0x42240000, v0
	v_fma_f32 v103, v81, |v14|, v103
	v_sub_f32_e32 v14, 0x41200000, v0
	ds_read_b64_tr_b16 v[208:209], v193 offset:0x1400
	ds_read_b64_tr_b16 v[210:211], v193 offset:0x1c00
	s_waitcnt lgkmcnt(6)
	v_mfma_f32_32x32x16_bf16 v[48:63], v[10:13], v[212:215], v[48:63]
	v_fma_f32 v119, v81, |v15|, v119
	v_sub_f32_e32 v15, 0x42280000, v0
	v_fma_f32 v104, v81, |v14|, v104
	v_sub_f32_e32 v14, 0x41300000, v0
	ds_read_b64_tr_b16 v[212:213], v193 offset:0x2400
	ds_read_b64_tr_b16 v[214:215], v193 offset:0x2c00
	ds_read_b64_tr_b16 v[216:217], v193 offset:0x3400
	ds_read_b64_tr_b16 v[218:219], v193 offset:0x3c00
	s_waitcnt lgkmcnt(8)
	v_mfma_f32_32x32x16_bf16 v[48:63], v[162:165], v[220:223], v[48:63]
	v_fma_f32 v120, v81, |v15|, v120
	v_sub_f32_e32 v15, 0x422c0000, v0
	v_fma_f32 v105, v81, |v14|, v105
	v_sub_f32_e32 v14, 0x41800000, v0
	s_waitcnt lgkmcnt(6)
	v_mfma_f32_32x32x16_bf16 v[32:47], v[2:5], v[204:207], v[32:47]
	v_fma_f32 v121, v81, |v15|, v121
	v_sub_f32_e32 v15, 0x42400000, v0
	v_fma_f32 v106, v81, |v14|, v106
	v_sub_f32_e32 v14, 0x41880000, v0
	ds_read_b64_tr_b16 v[204:205], v193 offset:0x600
	ds_read_b64_tr_b16 v[206:207], v193 offset:0xe00
	s_waitcnt lgkmcnt(6)
	v_mfma_f32_32x32x16_bf16 v[32:47], v[6:9], v[208:211], v[32:47]
	v_fma_f32 v122, v81, |v15|, v122
	v_sub_f32_e32 v15, 0x42440000, v0
	v_fma_f32 v107, v81, |v14|, v107
	v_sub_f32_e32 v14, 0x41900000, v0
	ds_read_b64_tr_b16 v[208:209], v193 offset:0x1600
	ds_read_b64_tr_b16 v[210:211], v193 offset:0x1e00
	s_waitcnt lgkmcnt(6)
	v_mfma_f32_32x32x16_bf16 v[32:47], v[10:13], v[212:215], v[32:47]
	v_fma_f32 v123, v81, |v15|, v123
	v_sub_f32_e32 v15, 0x42480000, v0
	v_fma_f32 v108, v81, |v14|, v108
	v_sub_f32_e32 v14, 0x41980000, v0
	ds_read_b64_tr_b16 v[212:213], v193 offset:0x2600
	ds_read_b64_tr_b16 v[214:215], v193 offset:0x2e00
	ds_read_b64_tr_b16 v[220:221], v193 offset:0x3600
	ds_read_b64_tr_b16 v[222:223], v193 offset:0x3e00
	s_waitcnt lgkmcnt(8)
	v_mfma_f32_32x32x16_bf16 v[32:47], v[162:165], v[216:219], v[32:47]
	v_fma_f32 v124, v81, |v15|, v124
	v_sub_f32_e32 v15, 0x424c0000, v0
	v_fma_f32 v109, v81, |v14|, v109
	v_sub_f32_e32 v14, 0x41c00000, v0
	s_waitcnt lgkmcnt(6)
	v_mfma_f32_32x32x16_bf16 v[16:31], v[2:5], v[204:207], v[16:31]
	v_fma_f32 v125, v81, |v15|, v125
	v_sub_f32_e32 v15, 0x42600000, v0
	v_fma_f32 v110, v81, |v14|, v110
	v_sub_f32_e32 v14, 0x41c80000, v0
	s_waitcnt lgkmcnt(4)
	v_mfma_f32_32x32x16_bf16 v[16:31], v[6:9], v[208:211], v[16:31]
	v_fma_f32 v126, v81, |v15|, v126
	v_sub_f32_e32 v15, 0x42640000, v0
	v_fma_f32 v111, v81, |v14|, v111
	v_sub_f32_e32 v14, 0x41d00000, v0
	s_waitcnt lgkmcnt(2)
	v_mfma_f32_32x32x16_bf16 v[16:31], v[10:13], v[212:215], v[16:31]
	v_fma_f32 v127, v81, |v15|, v127
	v_sub_f32_e32 v15, 0x42680000, v0
	v_fma_f32 v112, v81, |v14|, v112
	v_sub_f32_e32 v14, 0x41d80000, v0
	s_waitcnt lgkmcnt(0)
	v_mfma_f32_32x32x16_bf16 v[16:31], v[162:165], v[220:223], v[16:31]
	v_sub_f32_e32 v0, 0x426c0000, v0
	v_fma_f32 v128, v81, |v15|, v128
	v_fma_f32 v113, v81, |v14|, v113
	v_fma_f32 v129, v81, |v0|, v129
	s_barrier
	s_branch .Lafter_bias_1
